# nt hint also on the residual-base loads of the in-place residual GEMM epilogues (read once, then overwritten)
# baseline (speedup 1.0000x reference)
;     __device__ __forceinline__ void operator()(const f32x4 (&acc)[2][2][4][2], const Unit& u, int wr, int wc, int fr, int fq) const {
;         const int col0 = u.pn * BM + wc * 32 + 4 * fq;
; #pragma unroll
;         for (int ai = 0; ai < 2; ++ai) { if (ai * HALF >= rowmul) break;
; #pragma unroll
;             for (int m = 0; m < 4; ++m) { const size_t off = (size_t)(u.pm * rowmul + ai * HALF + wr * 64 + m * 16 + fr) * ldc + col0;
; #pragma unroll
;                 for (int bj = 0; bj < 2; ++bj)
; #pragma unroll
;                     for (int n = 0; n < 2; ++n) { const f32x4 bs = *(const f32x4*)(base + off + bj * HALF + n * 16);
;                         *(f32x4*)(out + off + bj * HALF + n * 16) = bs + acc[ai][bj][m][n] * alpha; } } }
.LBB0_329:
	s_lshl_b32 s0, s44, 8
	v_add_u32_e32 v140, s0, v151
	v_lshl_or_b32 v138, s45, 8, v156
	v_ashrrev_i32_e32 v141, 31, v140
	v_ashrrev_i32_e32 v139, 31, v138
	v_lshlrev_b64 v[158:159], 10, v[140:141]
	v_lshl_add_u64 v[158:159], v[158:159], 0, v[138:139]
	v_lshlrev_b64 v[162:163], 2, v[158:159]
	v_lshl_add_u64 v[164:165], s[14:15], 0, v[162:163]
	global_load_dwordx4 v[158:161], v[164:165], off nt
	v_lshl_add_u64 v[162:163], s[8:9], 0, v[162:163]
	s_and_b64 vcc, exec, s[4:5]
	s_mov_b64 s[4:5], -1
	s_waitcnt vmcnt(0)
	v_pk_fma_f32 v[128:129], v[128:129], 0.5, v[160:161] op_sel_hi:[1,0,1]
	v_pk_fma_f32 v[126:127], v[126:127], 0.5, v[158:159] op_sel_hi:[1,0,1]
	global_store_dwordx4 v[162:163], v[126:129], off
	global_load_dwordx4 v[126:129], v[164:165], off offset:64 nt
	s_waitcnt vmcnt(0)
	v_pk_fma_f32 v[124:125], v[124:125], 0.5, v[128:129] op_sel_hi:[1,0,1]
	v_pk_fma_f32 v[122:123], v[122:123], 0.5, v[126:127] op_sel_hi:[1,0,1]
	global_store_dwordx4 v[162:163], v[122:125], off offset:64
	global_load_dwordx4 v[122:125], v[164:165], off offset:512 nt
	s_waitcnt vmcnt(0)
	v_pk_fma_f32 v[120:121], v[120:121], 0.5, v[124:125] op_sel_hi:[1,0,1]
	v_pk_fma_f32 v[118:119], v[118:119], 0.5, v[122:123] op_sel_hi:[1,0,1]
	global_store_dwordx4 v[162:163], v[118:121], off offset:512
	global_load_dwordx4 v[118:121], v[164:165], off offset:576 nt
	v_add_u32_e32 v122, s0, v153
	v_ashrrev_i32_e32 v123, 31, v122
	v_lshlrev_b64 v[122:123], 10, v[122:123]
	v_lshl_add_u64 v[122:123], v[122:123], 0, v[138:139]
	v_lshlrev_b64 v[122:123], 2, v[122:123]
	v_lshl_add_u64 v[124:125], s[14:15], 0, v[122:123]
	s_waitcnt vmcnt(0)
	v_pk_fma_f32 v[108:109], v[108:109], 0.5, v[120:121] op_sel_hi:[1,0,1]
	v_pk_fma_f32 v[106:107], v[106:107], 0.5, v[118:119] op_sel_hi:[1,0,1]
	global_store_dwordx4 v[162:163], v[106:109], off offset:576
	global_load_dwordx4 v[106:109], v[124:125], off nt
	v_lshl_add_u64 v[118:119], s[8:9], 0, v[122:123]
	s_waitcnt vmcnt(0)
	v_pk_fma_f32 v[108:109], v[116:117], 0.5, v[108:109] op_sel_hi:[1,0,1]
	v_pk_fma_f32 v[106:107], v[114:115], 0.5, v[106:107] op_sel_hi:[1,0,1]
	global_store_dwordx4 v[118:119], v[106:109], off
	global_load_dwordx4 v[106:109], v[124:125], off offset:64 nt
	s_waitcnt vmcnt(0)
	v_pk_fma_f32 v[108:109], v[112:113], 0.5, v[108:109] op_sel_hi:[1,0,1]
	v_pk_fma_f32 v[106:107], v[110:111], 0.5, v[106:107] op_sel_hi:[1,0,1]
	global_store_dwordx4 v[118:119], v[106:109], off offset:64
	global_load_dwordx4 v[106:109], v[124:125], off offset:512 nt
	s_waitcnt vmcnt(0)
	v_pk_fma_f32 v[104:105], v[104:105], 0.5, v[108:109] op_sel_hi:[1,0,1]
	v_pk_fma_f32 v[102:103], v[102:103], 0.5, v[106:107] op_sel_hi:[1,0,1]
	global_store_dwordx4 v[118:119], v[102:105], off offset:512
	global_load_dwordx4 v[102:105], v[124:125], off offset:576 nt
	v_add_u32_e32 v106, s0, v154
	v_ashrrev_i32_e32 v107, 31, v106
	v_lshlrev_b64 v[106:107], 10, v[106:107]
	v_lshl_add_u64 v[106:107], v[106:107], 0, v[138:139]
	v_lshlrev_b64 v[106:107], 2, v[106:107]
	v_lshl_add_u64 v[108:109], s[14:15], 0, v[106:107]
	s_waitcnt vmcnt(0)
	v_pk_fma_f32 v[92:93], v[92:93], 0.5, v[104:105] op_sel_hi:[1,0,1]
	v_pk_fma_f32 v[90:91], v[90:91], 0.5, v[102:103] op_sel_hi:[1,0,1]
	global_store_dwordx4 v[118:119], v[90:93], off offset:576
	global_load_dwordx4 v[90:93], v[108:109], off nt
	v_lshl_add_u64 v[102:103], s[8:9], 0, v[106:107]
	s_waitcnt vmcnt(0)
	v_pk_fma_f32 v[92:93], v[100:101], 0.5, v[92:93] op_sel_hi:[1,0,1]
	v_pk_fma_f32 v[90:91], v[98:99], 0.5, v[90:91] op_sel_hi:[1,0,1]
	global_store_dwordx4 v[102:103], v[90:93], off
	global_load_dwordx4 v[90:93], v[108:109], off offset:64 nt
	s_waitcnt vmcnt(0)
	v_pk_fma_f32 v[92:93], v[96:97], 0.5, v[92:93] op_sel_hi:[1,0,1]
	v_pk_fma_f32 v[90:91], v[94:95], 0.5, v[90:91] op_sel_hi:[1,0,1]
	global_store_dwordx4 v[102:103], v[90:93], off offset:64
	global_load_dwordx4 v[90:93], v[108:109], off offset:512 nt
	s_waitcnt vmcnt(0)
	v_pk_fma_f32 v[88:89], v[88:89], 0.5, v[92:93] op_sel_hi:[1,0,1]
	v_pk_fma_f32 v[86:87], v[86:87], 0.5, v[90:91] op_sel_hi:[1,0,1]
	global_store_dwordx4 v[102:103], v[86:89], off offset:512
	global_load_dwordx4 v[86:89], v[108:109], off offset:576 nt
	v_add_u32_e32 v90, s0, v155
	v_ashrrev_i32_e32 v91, 31, v90
	v_lshlrev_b64 v[90:91], 10, v[90:91]
	v_lshl_add_u64 v[90:91], v[90:91], 0, v[138:139]
	v_lshlrev_b64 v[90:91], 2, v[90:91]
	v_lshl_add_u64 v[92:93], s[14:15], 0, v[90:91]
	s_waitcnt vmcnt(0)
	v_pk_fma_f32 v[76:77], v[76:77], 0.5, v[88:89] op_sel_hi:[1,0,1]
	v_pk_fma_f32 v[74:75], v[74:75], 0.5, v[86:87] op_sel_hi:[1,0,1]
	global_store_dwordx4 v[102:103], v[74:77], off offset:576
	global_load_dwordx4 v[74:77], v[92:93], off nt
	v_lshl_add_u64 v[86:87], s[8:9], 0, v[90:91]
	s_waitcnt vmcnt(0)
	v_pk_fma_f32 v[76:77], v[84:85], 0.5, v[76:77] op_sel_hi:[1,0,1]
	v_pk_fma_f32 v[74:75], v[82:83], 0.5, v[74:75] op_sel_hi:[1,0,1]
	global_store_dwordx4 v[86:87], v[74:77], off
	global_load_dwordx4 v[74:77], v[92:93], off offset:64 nt
	s_waitcnt vmcnt(0)
	v_pk_fma_f32 v[76:77], v[80:81], 0.5, v[76:77] op_sel_hi:[1,0,1]
	v_pk_fma_f32 v[74:75], v[78:79], 0.5, v[74:75] op_sel_hi:[1,0,1]
	global_store_dwordx4 v[86:87], v[74:77], off offset:64
	global_load_dwordx4 v[74:77], v[92:93], off offset:512 nt
	s_waitcnt vmcnt(0)
	v_pk_fma_f32 v[72:73], v[72:73], 0.5, v[76:77] op_sel_hi:[1,0,1]
	v_pk_fma_f32 v[70:71], v[70:71], 0.5, v[74:75] op_sel_hi:[1,0,1]
	global_store_dwordx4 v[86:87], v[70:73], off offset:512
	global_load_dwordx4 v[70:73], v[92:93], off offset:576 nt
	v_add_u32_e32 v74, 0x80, v140
	v_ashrrev_i32_e32 v75, 31, v74
	v_lshlrev_b64 v[74:75], 10, v[74:75]
	v_lshl_add_u64 v[74:75], v[74:75], 0, v[138:139]
	v_lshlrev_b64 v[74:75], 2, v[74:75]
	v_lshl_add_u64 v[76:77], s[14:15], 0, v[74:75]
	s_waitcnt vmcnt(0)
;     __device__ __forceinline__ void operator()(const f32x4 (&acc)[2][2][4][2], const Unit& u, int wr, int wc, int fr, int fq) const {
;         const int col0 = u.pn * BM + wc * 32 + 4 * fq;
; #pragma unroll
;         for (int ai = 0; ai < 2; ++ai) { if (ai * HALF >= rowmul) break;
; #pragma unroll
;             for (int m = 0; m < 4; ++m) { const size_t off = (size_t)(u.pm * rowmul + ai * HALF + wr * 64 + m * 16 + fr) * ldc + col0;
; #pragma unroll
;                 for (int bj = 0; bj < 2; ++bj)
; #pragma unroll
;                     for (int n = 0; n < 2; ++n) { const f32x4 bs = *(const f32x4*)(base + off + bj * HALF + n * 16);
;                         *(f32x4*)(out + off + bj * HALF + n * 16) = bs + acc[ai][bj][m][n] * alpha; } } }
	v_pk_fma_f32 v[68:69], v[68:69], 0.5, v[72:73] op_sel_hi:[1,0,1]
	v_pk_fma_f32 v[66:67], v[66:67], 0.5, v[70:71] op_sel_hi:[1,0,1]
	global_store_dwordx4 v[86:87], v[66:69], off offset:576
	global_load_dwordx4 v[66:69], v[76:77], off nt
	v_lshl_add_u64 v[70:71], s[8:9], 0, v[74:75]
	s_waitcnt vmcnt(0)
	v_pk_fma_f32 v[64:65], v[64:65], 0.5, v[68:69] op_sel_hi:[1,0,1]
	v_pk_fma_f32 v[62:63], v[62:63], 0.5, v[66:67] op_sel_hi:[1,0,1]
	global_store_dwordx4 v[70:71], v[62:65], off
	global_load_dwordx4 v[62:65], v[76:77], off offset:64 nt
	s_waitcnt vmcnt(0)
	v_pk_fma_f32 v[60:61], v[60:61], 0.5, v[64:65] op_sel_hi:[1,0,1]
	v_pk_fma_f32 v[58:59], v[58:59], 0.5, v[62:63] op_sel_hi:[1,0,1]
	global_store_dwordx4 v[70:71], v[58:61], off offset:64
	global_load_dwordx4 v[58:61], v[76:77], off offset:512 nt
	s_waitcnt vmcnt(0)
	v_pk_fma_f32 v[56:57], v[56:57], 0.5, v[60:61] op_sel_hi:[1,0,1]
	v_pk_fma_f32 v[54:55], v[54:55], 0.5, v[58:59] op_sel_hi:[1,0,1]
	global_store_dwordx4 v[70:71], v[54:57], off offset:512
	global_load_dwordx4 v[54:57], v[76:77], off offset:576 nt
	v_add_u32_e32 v58, 0x90, v140
	v_ashrrev_i32_e32 v59, 31, v58
	v_lshlrev_b64 v[58:59], 10, v[58:59]
	v_lshl_add_u64 v[58:59], v[58:59], 0, v[138:139]
	v_lshlrev_b64 v[58:59], 2, v[58:59]
	v_lshl_add_u64 v[60:61], s[14:15], 0, v[58:59]
	s_waitcnt vmcnt(0)
	v_pk_fma_f32 v[44:45], v[44:45], 0.5, v[56:57] op_sel_hi:[1,0,1]
	v_pk_fma_f32 v[42:43], v[42:43], 0.5, v[54:55] op_sel_hi:[1,0,1]
	global_store_dwordx4 v[70:71], v[42:45], off offset:576
	global_load_dwordx4 v[42:45], v[60:61], off nt
	v_lshl_add_u64 v[54:55], s[8:9], 0, v[58:59]
	s_waitcnt vmcnt(0)
	v_pk_fma_f32 v[44:45], v[52:53], 0.5, v[44:45] op_sel_hi:[1,0,1]
	v_pk_fma_f32 v[42:43], v[50:51], 0.5, v[42:43] op_sel_hi:[1,0,1]
	global_store_dwordx4 v[54:55], v[42:45], off
	global_load_dwordx4 v[42:45], v[60:61], off offset:64 nt
	s_waitcnt vmcnt(0)
	v_pk_fma_f32 v[44:45], v[48:49], 0.5, v[44:45] op_sel_hi:[1,0,1]
	v_pk_fma_f32 v[42:43], v[46:47], 0.5, v[42:43] op_sel_hi:[1,0,1]
	global_store_dwordx4 v[54:55], v[42:45], off offset:64
	global_load_dwordx4 v[42:45], v[60:61], off offset:512 nt
	s_waitcnt vmcnt(0)
	v_pk_fma_f32 v[40:41], v[40:41], 0.5, v[44:45] op_sel_hi:[1,0,1]
	v_pk_fma_f32 v[38:39], v[38:39], 0.5, v[42:43] op_sel_hi:[1,0,1]
	global_store_dwordx4 v[54:55], v[38:41], off offset:512
	global_load_dwordx4 v[38:41], v[60:61], off offset:576 nt
	v_add_u32_e32 v42, 0xa0, v140
	v_ashrrev_i32_e32 v43, 31, v42
	v_lshlrev_b64 v[42:43], 10, v[42:43]
	v_lshl_add_u64 v[42:43], v[42:43], 0, v[138:139]
	v_lshlrev_b64 v[42:43], 2, v[42:43]
	v_lshl_add_u64 v[44:45], s[14:15], 0, v[42:43]
	s_waitcnt vmcnt(0)
	v_pk_fma_f32 v[28:29], v[28:29], 0.5, v[40:41] op_sel_hi:[1,0,1]
	v_pk_fma_f32 v[26:27], v[26:27], 0.5, v[38:39] op_sel_hi:[1,0,1]
	global_store_dwordx4 v[54:55], v[26:29], off offset:576
	global_load_dwordx4 v[26:29], v[44:45], off nt
	v_lshl_add_u64 v[38:39], s[8:9], 0, v[42:43]
	s_waitcnt vmcnt(0)
	v_pk_fma_f32 v[28:29], v[36:37], 0.5, v[28:29] op_sel_hi:[1,0,1]
	v_pk_fma_f32 v[26:27], v[34:35], 0.5, v[26:27] op_sel_hi:[1,0,1]
	global_store_dwordx4 v[38:39], v[26:29], off
	global_load_dwordx4 v[26:29], v[44:45], off offset:64 nt
	s_waitcnt vmcnt(0)
	v_pk_fma_f32 v[28:29], v[32:33], 0.5, v[28:29] op_sel_hi:[1,0,1]
	v_pk_fma_f32 v[26:27], v[30:31], 0.5, v[26:27] op_sel_hi:[1,0,1]
	global_store_dwordx4 v[38:39], v[26:29], off offset:64
	global_load_dwordx4 v[26:29], v[44:45], off offset:512 nt
	s_waitcnt vmcnt(0)
	v_pk_fma_f32 v[24:25], v[24:25], 0.5, v[28:29] op_sel_hi:[1,0,1]
	v_pk_fma_f32 v[22:23], v[22:23], 0.5, v[26:27] op_sel_hi:[1,0,1]
	global_store_dwordx4 v[38:39], v[22:25], off offset:512
	global_load_dwordx4 v[22:25], v[44:45], off offset:576 nt
	v_add_u32_e32 v26, 0xb0, v140
	v_ashrrev_i32_e32 v27, 31, v26
	v_lshlrev_b64 v[26:27], 10, v[26:27]
	v_lshl_add_u64 v[26:27], v[26:27], 0, v[138:139]
	v_lshlrev_b64 v[26:27], 2, v[26:27]
	v_lshl_add_u64 v[28:29], s[14:15], 0, v[26:27]
	s_waitcnt vmcnt(0)
	v_pk_fma_f32 v[12:13], v[12:13], 0.5, v[24:25] op_sel_hi:[1,0,1]
	v_pk_fma_f32 v[10:11], v[10:11], 0.5, v[22:23] op_sel_hi:[1,0,1]
	global_store_dwordx4 v[38:39], v[10:13], off offset:576
	global_load_dwordx4 v[10:13], v[28:29], off nt
	v_lshl_add_u64 v[22:23], s[8:9], 0, v[26:27]
	s_waitcnt vmcnt(0)
	v_pk_fma_f32 v[12:13], v[20:21], 0.5, v[12:13] op_sel_hi:[1,0,1]
	v_pk_fma_f32 v[10:11], v[18:19], 0.5, v[10:11] op_sel_hi:[1,0,1]
	global_store_dwordx4 v[22:23], v[10:13], off
	global_load_dwordx4 v[10:13], v[28:29], off offset:64 nt
	s_waitcnt vmcnt(0)
	v_pk_fma_f32 v[12:13], v[16:17], 0.5, v[12:13] op_sel_hi:[1,0,1]
	v_pk_fma_f32 v[10:11], v[14:15], 0.5, v[10:11] op_sel_hi:[1,0,1]
	global_store_dwordx4 v[22:23], v[10:13], off offset:64
	global_load_dwordx4 v[10:13], v[28:29], off offset:512 nt
	s_waitcnt vmcnt(0)
	v_pk_fma_f32 v[8:9], v[8:9], 0.5, v[12:13] op_sel_hi:[1,0,1]
	v_pk_fma_f32 v[6:7], v[6:7], 0.5, v[10:11] op_sel_hi:[1,0,1]
	global_store_dwordx4 v[22:23], v[6:9], off offset:512
	global_load_dwordx4 v[6:9], v[28:29], off offset:576 nt
	s_waitcnt vmcnt(0)
	v_pk_fma_f32 v[4:5], v[4:5], 0.5, v[8:9] op_sel_hi:[1,0,1]
	v_pk_fma_f32 v[2:3], v[2:3], 0.5, v[6:7] op_sel_hi:[1,0,1]
	global_store_dwordx4 v[22:23], v[2:5], off offset:576
	s_cbranch_vccnz .LBB0_314
	s_andn2_b64 vcc, exec, s[10:11]
	s_cbranch_vccnz .LBB0_313
	s_barrier
	s_branch .LBB0_313

;     __device__ __forceinline__ void operator()(const f32x4 (&acc)[2][2][4][2], const Unit& u, int wr, int wc, int fr, int fq) const {
;         const int col0 = u.pn * BM + wc * 32 + 4 * fq;
; #pragma unroll
;         for (int ai = 0; ai < 2; ++ai) { if (ai * HALF >= rowmul) break;
; #pragma unroll
;             for (int m = 0; m < 4; ++m) { const size_t off = (size_t)(u.pm * rowmul + ai * HALF + wr * 64 + m * 16 + fr) * ldc + col0;
; #pragma unroll
;                 for (int bj = 0; bj < 2; ++bj)
; #pragma unroll
;                     for (int n = 0; n < 2; ++n) { const f32x4 bs = *(const f32x4*)(base + off + bj * HALF + n * 16);
;                         *(f32x4*)(out + off + bj * HALF + n * 16) = bs + acc[ai][bj][m][n] * alpha; } } }
.LBB0_355:
	s_lshl_b32 s15, s22, 7
	v_add_u32_e32 v80, s15, v72
	v_lshl_or_b32 v70, s23, 8, v77
	v_ashrrev_i32_e32 v81, 31, v80
	v_ashrrev_i32_e32 v71, 31, v70
	v_lshlrev_b64 v[80:81], 12, v[80:81]
	v_lshl_add_u64 v[80:81], s[8:9], 0, v[80:81]
	v_lshlrev_b64 v[70:71], 2, v[70:71]
	v_lshl_add_u64 v[84:85], v[80:81], 0, v[70:71]
	global_load_dwordx4 v[80:83], v[84:85], off nt
	s_mov_b64 s[22:23], -1
	s_andn2_b64 vcc, exec, s[4:5]
	s_waitcnt vmcnt(0)
	v_pk_add_f32 v[64:65], v[64:65], v[82:83]
	v_pk_add_f32 v[62:63], v[62:63], v[80:81]
	global_store_dwordx4 v[84:85], v[62:65], off
	global_load_dwordx4 v[62:65], v[84:85], off offset:64 nt
	s_waitcnt vmcnt(0)
	v_pk_add_f32 v[60:61], v[60:61], v[64:65]
	v_pk_add_f32 v[58:59], v[58:59], v[62:63]
	global_store_dwordx4 v[84:85], v[58:61], off offset:64
	global_load_dwordx4 v[58:61], v[84:85], off offset:512 nt
	s_waitcnt vmcnt(0)
	v_pk_add_f32 v[56:57], v[56:57], v[60:61]
	v_pk_add_f32 v[54:55], v[54:55], v[58:59]
	global_store_dwordx4 v[84:85], v[54:57], off offset:512
	global_load_dwordx4 v[54:57], v[84:85], off offset:576 nt
	s_waitcnt vmcnt(0)
	v_pk_add_f32 v[52:53], v[52:53], v[56:57]
	v_pk_add_f32 v[50:51], v[50:51], v[54:55]
	global_store_dwordx4 v[84:85], v[50:53], off offset:576
	s_nop 1
	v_add_u32_e32 v50, s15, v74
	v_ashrrev_i32_e32 v51, 31, v50
	v_lshlrev_b64 v[50:51], 12, v[50:51]
	v_lshl_add_u64 v[50:51], s[8:9], 0, v[50:51]
	v_lshl_add_u64 v[54:55], v[50:51], 0, v[70:71]
	global_load_dwordx4 v[50:53], v[54:55], off nt
	s_waitcnt vmcnt(0)
	v_pk_add_f32 v[48:49], v[48:49], v[52:53]
	v_pk_add_f32 v[46:47], v[46:47], v[50:51]
	global_store_dwordx4 v[54:55], v[46:49], off
	global_load_dwordx4 v[46:49], v[54:55], off offset:64 nt
	s_waitcnt vmcnt(0)
	v_pk_add_f32 v[44:45], v[44:45], v[48:49]
	v_pk_add_f32 v[42:43], v[42:43], v[46:47]
	global_store_dwordx4 v[54:55], v[42:45], off offset:64
	global_load_dwordx4 v[42:45], v[54:55], off offset:512 nt
	s_waitcnt vmcnt(0)
	v_pk_add_f32 v[40:41], v[40:41], v[44:45]
	v_pk_add_f32 v[38:39], v[38:39], v[42:43]
	global_store_dwordx4 v[54:55], v[38:41], off offset:512
	global_load_dwordx4 v[38:41], v[54:55], off offset:576 nt
	s_waitcnt vmcnt(0)
	v_pk_add_f32 v[36:37], v[36:37], v[40:41]
	v_pk_add_f32 v[34:35], v[34:35], v[38:39]
	global_store_dwordx4 v[54:55], v[34:37], off offset:576
	s_nop 1
	v_add_u32_e32 v34, s15, v75
	v_ashrrev_i32_e32 v35, 31, v34
	v_lshlrev_b64 v[34:35], 12, v[34:35]
	v_lshl_add_u64 v[34:35], s[8:9], 0, v[34:35]
	v_lshl_add_u64 v[38:39], v[34:35], 0, v[70:71]
	global_load_dwordx4 v[34:37], v[38:39], off nt
	s_waitcnt vmcnt(0)
	v_pk_add_f32 v[32:33], v[32:33], v[36:37]
	v_pk_add_f32 v[30:31], v[30:31], v[34:35]
	global_store_dwordx4 v[38:39], v[30:33], off
	global_load_dwordx4 v[30:33], v[38:39], off offset:64 nt
	s_waitcnt vmcnt(0)
	v_pk_add_f32 v[28:29], v[28:29], v[32:33]
	v_pk_add_f32 v[26:27], v[26:27], v[30:31]
	global_store_dwordx4 v[38:39], v[26:29], off offset:64
	global_load_dwordx4 v[26:29], v[38:39], off offset:512 nt
	s_waitcnt vmcnt(0)
	v_pk_add_f32 v[24:25], v[24:25], v[28:29]
	v_pk_add_f32 v[22:23], v[22:23], v[26:27]
	global_store_dwordx4 v[38:39], v[22:25], off offset:512
	global_load_dwordx4 v[22:25], v[38:39], off offset:576 nt
	s_waitcnt vmcnt(0)
	v_pk_add_f32 v[20:21], v[20:21], v[24:25]
	v_pk_add_f32 v[18:19], v[18:19], v[22:23]
	global_store_dwordx4 v[38:39], v[18:21], off offset:576
	s_nop 1
	v_add_u32_e32 v18, s15, v76
	v_ashrrev_i32_e32 v19, 31, v18
	v_lshlrev_b64 v[18:19], 12, v[18:19]
	v_lshl_add_u64 v[18:19], s[8:9], 0, v[18:19]
	v_lshl_add_u64 v[18:19], v[18:19], 0, v[70:71]
	global_load_dwordx4 v[20:23], v[18:19], off nt
	s_waitcnt vmcnt(0)
	v_pk_add_f32 v[16:17], v[16:17], v[22:23]
	v_pk_add_f32 v[14:15], v[14:15], v[20:21]
	global_store_dwordx4 v[18:19], v[14:17], off
	global_load_dwordx4 v[14:17], v[18:19], off offset:64 nt
	s_waitcnt vmcnt(0)
	v_pk_add_f32 v[12:13], v[12:13], v[16:17]
	v_pk_add_f32 v[10:11], v[10:11], v[14:15]
	global_store_dwordx4 v[18:19], v[10:13], off offset:64
	global_load_dwordx4 v[10:13], v[18:19], off offset:512 nt
	s_waitcnt vmcnt(0)
	v_pk_add_f32 v[8:9], v[8:9], v[12:13]
	v_pk_add_f32 v[6:7], v[6:7], v[10:11]
	global_store_dwordx4 v[18:19], v[6:9], off offset:512
	global_load_dwordx4 v[6:9], v[18:19], off offset:576 nt
	s_waitcnt vmcnt(0)
	v_pk_add_f32 v[4:5], v[4:5], v[8:9]
	v_pk_add_f32 v[2:3], v[2:3], v[6:7]
	global_store_dwordx4 v[18:19], v[2:5], off offset:576
	s_cbranch_vccnz .LBB0_344
	s_andn2_b64 vcc, exec, s[6:7]
	s_cbranch_vccnz .LBB0_343
	s_barrier
	s_branch .LBB0_343
